# P1 tile order: slot permutation per (XCD, round) to spread sigmoid-gate tiles evenly over workgroups (same tile set per XCD and round)
# baseline (speedup 1.0000x reference)
.Lk1_wjb:
	s_waitcnt lgkmcnt(0)
	s_barrier
	s_waitcnt lgkmcnt(0)
	v_mfma_f32_16x16x32_bf16 v[120:123], v[144:147], v[180:183], 0
	v_mfma_f32_16x16x32_bf16 v[116:119], v[152:155], v[180:183], 0
	v_mfma_f32_16x16x32_bf16 v[104:107], v[144:147], v[188:191], 0
	v_mfma_f32_16x16x32_bf16 v[100:103], v[152:155], v[188:191], 0
	v_mfma_f32_16x16x32_bf16 v[88:91], v[144:147], v[206:209], 0
	v_mfma_f32_16x16x32_bf16 v[84:87], v[152:155], v[206:209], 0
	v_mfma_f32_16x16x32_bf16 v[72:75], v[144:147], v[214:217], 0
	v_mfma_f32_16x16x32_bf16 v[68:71], v[152:155], v[214:217], 0
	v_mfma_f32_16x16x32_bf16 v[120:123], v[148:151], v[184:187], v[120:123]
	v_mfma_f32_16x16x32_bf16 v[116:119], v[160:163], v[184:187], v[116:119]
	v_mfma_f32_16x16x32_bf16 v[104:107], v[148:151], v[192:195], v[104:107]
	v_mfma_f32_16x16x32_bf16 v[100:103], v[160:163], v[192:195], v[100:103]
	v_mfma_f32_16x16x32_bf16 v[88:91], v[148:151], v[210:213], v[88:91]
	v_mfma_f32_16x16x32_bf16 v[84:87], v[160:163], v[210:213], v[84:87]
	v_mfma_f32_16x16x32_bf16 v[72:75], v[148:151], v[218:221], v[72:75]
	v_mfma_f32_16x16x32_bf16 v[68:71], v[160:163], v[218:221], v[68:71]
	v_mfma_f32_16x16x32_bf16 v[128:131], v[164:167], v[180:183], 0
	v_mfma_f32_16x16x32_bf16 v[124:127], v[172:175], v[180:183], 0
	v_mfma_f32_16x16x32_bf16 v[112:115], v[164:167], v[188:191], 0
	v_mfma_f32_16x16x32_bf16 v[108:111], v[172:175], v[188:191], 0
	v_mfma_f32_16x16x32_bf16 v[96:99], v[164:167], v[206:209], 0
	v_mfma_f32_16x16x32_bf16 v[92:95], v[172:175], v[206:209], 0
	v_mfma_f32_16x16x32_bf16 v[80:83], v[164:167], v[214:217], 0
	v_mfma_f32_16x16x32_bf16 v[76:79], v[172:175], v[214:217], 0
	v_mfma_f32_16x16x32_bf16 v[128:131], v[168:171], v[184:187], v[128:131]
	v_mfma_f32_16x16x32_bf16 v[124:127], v[176:179], v[184:187], v[124:127]
	v_mfma_f32_16x16x32_bf16 v[112:115], v[168:171], v[192:195], v[112:115]
	v_mfma_f32_16x16x32_bf16 v[108:111], v[176:179], v[192:195], v[108:111]
	v_mfma_f32_16x16x32_bf16 v[96:99], v[168:171], v[210:213], v[96:99]
	v_mfma_f32_16x16x32_bf16 v[92:95], v[176:179], v[210:213], v[92:95]
	v_mfma_f32_16x16x32_bf16 v[80:83], v[168:171], v[218:221], v[80:83]
	v_mfma_f32_16x16x32_bf16 v[76:79], v[176:179], v[218:221], v[76:79]
	s_barrier
	s_add_i32 s41, s41, s35
	v_lshl_add_u64 v[234:235], s[20:21], 0, v[134:135]
	s_mov_b32 m0, s41
	ds_read_b128 v[180:183], v158 offset:16384
	ds_read_b128 v[184:187], v158 offset:17408
	ds_read_b128 v[188:191], v158 offset:18432
	ds_read_b128 v[192:195], v158 offset:19456
	ds_read_b128 v[206:209], v158 offset:20480
	ds_read_b128 v[210:213], v158 offset:21504
	ds_read_b128 v[214:217], v158 offset:22528
	ds_read_b128 v[218:221], v158 offset:23552
	global_load_lds_dwordx4 v[234:235], off
	s_add_i32 m0, s41, 0x2000
	s_add_u32 s42, s20, 0x40000
	v_lshl_add_u64 v[236:237], s[20:21], 0, v[138:139]
	s_addc_u32 s43, s21, 0
	s_add_i32 s41, s55, s35
	global_load_lds_dwordx4 v[236:237], off
	v_lshl_add_u64 v[238:239], s[42:43], 0, v[134:135]
	s_mov_b32 m0, s41
	v_lshl_add_u64 v[240:241], s[22:23], 0, v[136:137]
	global_load_lds_dwordx4 v[238:239], off
	v_lshl_add_u64 v[238:239], s[42:43], 0, v[138:139]
	s_add_i32 m0, s41, 0x2000
	s_nop 0
	global_load_lds_dwordx4 v[238:239], off
	v_lshl_add_u64 v[238:239], s[22:23], 0, v[132:133]
	s_mov_b32 m0, s36
	s_nop 0
	global_load_lds_dwordx4 v[238:239], off
	s_mov_b32 m0, s37
	s_nop 0
	global_load_lds_dwordx4 v[240:241], off
	s_add_i32 s72, s72, 1
	s_mul_i32 s15, s72, s84
	s_mul_hi_u32 s17, s72, s83
	s_add_i32 s17, s17, s15
	s_mul_i32 s15, s72, s83
	s_add_u32 s62, s15, s2
	s_addc_u32 s63, s17, s93
	v_cmp_gt_i64_e32 vcc, s[62:63], v[202:203]
	v_cmp_lt_i64_e64 s[38:39], s[62:63], v[200:201]
	s_cbranch_vccnz .Lm1_nonext
	s_and_b32 s17, s62, 7
	s_lshr_b32 s15, s62, 3
	s_sub_u32 s63, s15, 32
	s_cmp_lt_u32 s63, 0x80
	s_cbranch_scc0 .Lp1perm_skip
	s_lshr_b32 s63, s63, 5
	s_mul_i32 s63, s63, 5
	s_mov_b32 s101, 0xb1bc6
	s_cmp_eq_u32 s17, 1
	s_cselect_b32 s101, 0x801b0, s101
	s_cmp_eq_u32 s17, 2
	s_cselect_b32 s101, 0x87a00, s101
	s_cmp_eq_u32 s17, 3
	s_cselect_b32 s101, 0x2e9b8, s101
	s_cmp_eq_u32 s17, 4
	s_cselect_b32 s101, 0x842d6, s101
	s_cmp_eq_u32 s17, 5
	s_cselect_b32 s101, 0xae3bd, s101
	s_cmp_eq_u32 s17, 6
	s_cselect_b32 s101, 0x71084, s101
	s_cmp_eq_u32 s17, 7
	s_cselect_b32 s101, 0x70300, s101
	s_lshr_b32 s101, s101, s63
	s_and_b32 s101, s101, 31
	s_xor_b32 s15, s15, s101
.Lp1perm_skip:
	s_mul_i32 s63, s17, 0xb3
	s_sub_i32 s101, s17, 6
	s_max_i32 s101, s101, 0
	s_sub_i32 s63, s63, s101
	s_add_i32 s15, s15, s63
	s_mul_hi_i32 s17, s15, 0x2e8ba2e9
	s_ashr_i32 s17, s17, 3
	s_mul_i32 s63, s17, 44
	s_sub_i32 s15, s15, s63
	s_lshl_b32 s17, s17, 1
	s_sub_i32 s63, 0x41, s17
	s_min_i32 s63, s63, 2
	s_sub_i32 s63, s63, 1
	s_lshr_b32 s54, s15, s63
	s_and_b32 s15, s15, s63
	s_add_i32 s56, s17, s15
